# resnorm row loops: residual-stream f32 stores use the nt (streaming) policy instead of sc1 write-through
# speedup vs baseline: 1.0411x; 1.0089x over previous
; __device__ __forceinline__ void st16_wt(void* p, u32x4 v) { asm volatile("global_store_dwordx4 %0, %1, off sc1\n\ts_nop 4" :: "v"(p), "v"(v) : "memory"); }
; __device__ __forceinline__ void resnorm_rows(const float* hin, const bf16_t* tmp, const float* g1, float* hout, const float* g2, bf16_t* xn, int gw, int NGW, int lane) {
;     for (int row = gw; row < NTOK; row += NGW) {
;         const u32x2* tr = (const u32x2*)(tmp + (size_t)row * DMODEL) + lane; f32x4 t[4]; float ss = 0.f;
; #pragma unroll
;         for (int j = 0; j < 4; ++j) { const u32x2 w = __builtin_nontemporal_load(tr + 64 * j); t[j] = (f32x4){bflo(w.x), bfhi(w.x), bflo(w.y), bfhi(w.y)}; ss += (t[j][0] * t[j][0] + t[j][1] * t[j][1]) + (t[j][2] * t[j][2] + t[j][3] * t[j][3]); }
;         const float rs = __builtin_amdgcn_rsqf(wave_sum(ss) * (1.f / DMODEL) + EPSN);
;         const f32x4* hr = (const f32x4*)(hin + (size_t)row * DMODEL) + lane; f32x4* ho = (f32x4*)(hout + (size_t)row * DMODEL) + lane; float s2 = 0.f;
; #pragma unroll
;         for (int j = 0; j < 4; ++j) { const f32x4 gg = ((const f32x4*)g1)[lane + 64 * j]; f32x4 h = __builtin_nontemporal_load(hr + 64 * j);
;             h[0] += t[j][0] * rs * gg[0]; h[1] += t[j][1] * rs * gg[1]; h[2] += t[j][2] * rs * gg[2]; h[3] += t[j][3] * rs * gg[3];
;             st16_wt(ho + 64 * j, __builtin_bit_cast(u32x4, h)); t[j] = h; s2 += (h[0] * h[0] + h[1] * h[1]) + (h[2] * h[2] + h[3] * h[3]); }
.Lrn_nopf_ph7:
	v_and_b32_e32 v35, 0xffff0000, v11
	v_and_b32_e32 v37, 0xffff0000, v10
	v_lshlrev_b32_e32 v34, 16, v11
	v_lshlrev_b32_e32 v36, 16, v10
	v_lshlrev_b32_e32 v41, 16, v13
	v_lshlrev_b32_e32 v40, 16, v12
	v_and_b32_e32 v43, 0xffff0000, v13
	v_and_b32_e32 v42, 0xffff0000, v12
	v_mov_b32_e32 v12, v37
	v_mov_b32_e32 v13, v35
	v_lshlrev_b32_e32 v44, 16, v23
	v_and_b32_e32 v45, 0xffff0000, v23
	v_lshlrev_b32_e32 v46, 16, v22
	v_and_b32_e32 v47, 0xffff0000, v22
	v_mov_b32_e32 v10, v36
	v_mov_b32_e32 v11, v34
	v_pk_mul_f32 v[22:23], v[42:43], v[42:43]
	v_pk_mul_f32 v[12:13], v[12:13], v[12:13]
	v_lshlrev_b32_e32 v48, 16, v25
	v_and_b32_e32 v49, 0xffff0000, v25
	v_lshlrev_b32_e32 v50, 16, v24
	v_and_b32_e32 v51, 0xffff0000, v24
	v_mul_f32_e32 v24, v45, v45
	v_mul_f32_e32 v52, v47, v47
	v_pk_fma_f32 v[22:23], v[40:41], v[40:41], v[22:23]
	v_pk_fma_f32 v[10:11], v[10:11], v[10:11], v[12:13]
	v_pk_mul_f32 v[54:55], v[48:49], v[48:49]
	v_pk_mul_f32 v[56:57], v[50:51], v[50:51]
	v_pk_fma_f32 v[24:25], v[44:45], v[44:45], v[24:25] op_sel_hi:[1,1,0]
	v_pk_fma_f32 v[52:53], v[46:47], v[46:47], v[52:53] op_sel_hi:[1,1,0]
	v_pk_add_f32 v[12:13], v[22:23], v[22:23] op_sel:[0,1] op_sel_hi:[1,0]
	v_pk_add_f32 v[10:11], v[10:11], v[10:11] op_sel:[0,1] op_sel_hi:[1,0]
	v_mov_b32_e32 v53, v54
	v_mov_b32_e32 v25, v55
	v_mov_b32_e32 v13, v57
	v_mov_b32_e32 v11, v56
	v_pk_add_f32 v[22:23], v[52:53], v[24:25]
	v_pk_add_f32 v[10:11], v[10:11], v[12:13]
	v_lshl_add_u64 v[54:55], s[8:9], 0, v[20:21]
	v_pk_add_f32 v[10:11], v[10:11], v[22:23]
	s_nop 0
	v_add_f32_e32 v10, v10, v11
	ds_bpermute_b32 v11, v26, v10
	s_waitcnt lgkmcnt(0)
	v_add_f32_e32 v10, v10, v11
	ds_bpermute_b32 v11, v27, v10
	s_waitcnt lgkmcnt(0)
	v_add_f32_e32 v10, v10, v11
	ds_bpermute_b32 v11, v28, v10
	s_waitcnt lgkmcnt(0)
	v_add_f32_e32 v10, v10, v11
	ds_bpermute_b32 v11, v29, v10
	s_waitcnt lgkmcnt(0)
	v_add_f32_e32 v10, v10, v11
	ds_bpermute_b32 v11, v30, v10
	s_waitcnt lgkmcnt(0)
	v_add_f32_e32 v10, v10, v11
	ds_bpermute_b32 v11, v31, v10
	s_waitcnt lgkmcnt(0)
	v_add_f32_e32 v10, v10, v11
	v_fmamk_f32 v10, v10, 0x3a800000, v32
	v_rsq_f32_e32 v52, v10
	s_nop 0
	v_pk_mul_f32 v[10:11], v[52:53], v[36:37] op_sel_hi:[0,1]
	v_pk_mul_f32 v[12:13], v[52:53], v[34:35] op_sel_hi:[0,1]
	v_pk_fma_f32 v[2:3], v[2:3], v[10:11], v[6:7]
	v_pk_fma_f32 v[4:5], v[4:5], v[12:13], v[8:9]
	v_pk_mul_f32 v[22:23], v[52:53], v[40:41] op_sel_hi:[0,1]
	global_store_dwordx4 v[54:55], v[2:5], off nt
	s_nop 4
	v_mov_b64_e32 v[6:7], v[120:121]
	v_mov_b64_e32 v[8:9], v[122:123]
	v_mov_b64_e32 v[10:11], v[124:125]
	v_mov_b64_e32 v[12:13], v[126:127]
	v_pk_mul_f32 v[36:37], v[52:53], v[42:43] op_sel_hi:[0,1]
	v_lshl_add_u64 v[34:35], v[54:55], 0, s[18:19]
	v_pk_mul_f32 v[42:43], v[52:53], v[48:49] op_sel_hi:[0,1]
	s_waitcnt vmcnt(1)
	v_mov_b32_e32 v24, v6
	v_mov_b32_e32 v25, v8
	v_mov_b32_e32 v40, v10
	v_mov_b32_e32 v41, v12
	v_mov_b32_e32 v8, v7
	v_mov_b32_e32 v12, v11
	v_pk_fma_f32 v[24:25], v[24:25], v[22:23], v[40:41]
	v_pk_fma_f32 v[22:23], v[8:9], v[36:37], v[12:13]
	v_mov_b32_e32 v6, v24
	v_mov_b32_e32 v7, v22
	v_mov_b32_e32 v8, v25
	v_mov_b32_e32 v9, v23
	global_store_dwordx4 v[34:35], v[6:9], off nt
	s_nop 4
	v_mov_b64_e32 v[6:7], v[128:129]
	v_mov_b64_e32 v[8:9], v[130:131]
	v_mov_b64_e32 v[10:11], v[132:133]
	v_mov_b64_e32 v[12:13], v[134:135]
	v_pk_mul_f32 v[36:37], v[52:53], v[46:47] op_sel_hi:[0,1]
	v_pk_mul_f32 v[40:41], v[52:53], v[44:45] op_sel_hi:[0,1]
	v_lshl_add_u64 v[34:35], v[54:55], 0, s[20:21]
	v_pk_fma_f32 v[6:7], v[6:7], v[36:37], v[10:11]
	v_pk_fma_f32 v[8:9], v[8:9], v[40:41], v[12:13]
	v_pk_mul_f32 v[40:41], v[52:53], v[50:51] op_sel_hi:[0,1]
	global_store_dwordx4 v[34:35], v[6:9], off nt
	s_nop 4
	v_mov_b64_e32 v[10:11], v[136:137]
	v_mov_b64_e32 v[12:13], v[138:139]
	v_mov_b64_e32 v[34:35], v[140:141]
	v_mov_b64_e32 v[36:37], v[142:143]
	v_lshl_add_u64 v[38:39], v[54:55], 0, s[22:23]
	v_pk_fma_f32 v[10:11], v[40:41], v[10:11], v[34:35]
	v_pk_fma_f32 v[12:13], v[42:43], v[12:13], v[36:37]
	s_nop 0
	global_store_dwordx4 v[38:39], v[10:13], off nt
	s_nop 4
	s_cbranch_vccnz .LBB0_1119
; __device__ __forceinline__ unsigned cvtpk(float lo, float hi) { typedef __bf16 bf2 __attribute__((ext_vector_type(2))); f32x2 v = {lo, hi}; bf2 b = __builtin_convertvector(v, bf2); return __builtin_bit_cast(unsigned, b); }
; __device__ __forceinline__ void resnorm_rows(const float* hin, const bf16_t* tmp, const float* g1, float* hout, const float* g2, bf16_t* xn, int gw, int NGW, int lane) {
;     ...
;         if (g2) {
;             const float r2 = __builtin_amdgcn_rsqf(wave_sum(s2) * (1.f / DMODEL) + EPSN);
;             u32x2* o = (u32x2*)(xn + (size_t)row * DMODEL) + lane;
; #pragma unroll
;             for (int j = 0; j < 4; ++j) { const f32x4 gg = ((const f32x4*)g2)[lane + 64 * j]; u32x2 w; w.x = cvtpk(t[j][0] * r2 * gg[0], t[j][1] * r2 * gg[1]); w.y = cvtpk(t[j][2] * r2 * gg[2], t[j][3] * r2 * gg[3]); o[64 * j] = w; }
;         }
	v_mov_b64_e32 v[34:35], v[144:145]
	v_mov_b64_e32 v[36:37], v[146:147]
	v_mov_b32_e32 v40, v3
	v_mov_b32_e32 v41, v5
	v_mov_b32_e32 v38, v2
	v_mov_b32_e32 v39, v4
	v_pk_mul_f32 v[42:43], v[22:23], v[22:23]
	v_pk_mul_f32 v[40:41], v[40:41], v[40:41]
	v_mul_f32_e32 v44, v8, v8
	v_mul_f32_e32 v50, v6, v6
	v_pk_fma_f32 v[42:43], v[24:25], v[24:25], v[42:43]
	v_pk_fma_f32 v[38:39], v[38:39], v[38:39], v[40:41]
	v_pk_mul_f32 v[46:47], v[10:11], v[10:11]
	v_pk_mul_f32 v[48:49], v[12:13], v[12:13]
	v_pk_fma_f32 v[44:45], v[8:9], v[8:9], v[44:45] op_sel_hi:[1,1,0]
	v_pk_fma_f32 v[50:51], v[6:7], v[6:7], v[50:51] op_sel_hi:[1,1,0]
	v_pk_add_f32 v[40:41], v[42:43], v[42:43] op_sel_hi:[0,1]
	v_pk_add_f32 v[38:39], v[38:39], v[38:39] op_sel_hi:[0,1]
	v_mov_b32_e32 v50, v46
	v_mov_b32_e32 v44, v47
	v_mov_b32_e32 v40, v49
	v_mov_b32_e32 v38, v48
	v_pk_add_f32 v[42:43], v[50:51], v[44:45]
	v_pk_add_f32 v[38:39], v[38:39], v[40:41]
	s_nop 0
	v_pk_add_f32 v[38:39], v[42:43], v[38:39]
	s_nop 0
	v_add_f32_e32 v33, v38, v39
	ds_bpermute_b32 v38, v26, v33
	s_waitcnt lgkmcnt(0)
	v_add_f32_e32 v33, v33, v38
	ds_bpermute_b32 v38, v27, v33
	s_waitcnt lgkmcnt(0)
	v_add_f32_e32 v33, v33, v38
	ds_bpermute_b32 v38, v28, v33
	s_waitcnt lgkmcnt(0)
	v_add_f32_e32 v33, v33, v38
	ds_bpermute_b32 v38, v29, v33
	s_waitcnt lgkmcnt(0)
	v_add_f32_e32 v33, v33, v38
	ds_bpermute_b32 v38, v30, v33
	s_waitcnt lgkmcnt(0)
	v_add_f32_e32 v33, v33, v38
	ds_bpermute_b32 v38, v31, v33
	s_waitcnt lgkmcnt(0)
	v_add_f32_e32 v33, v33, v38
	v_fmamk_f32 v33, v33, 0x3a800000, v32
	v_rsq_f32_e32 v38, v33
	s_nop 0
	v_pk_mul_f32 v[2:3], v[2:3], v[38:39] op_sel_hi:[1,0]
	v_pk_mul_f32 v[4:5], v[4:5], v[38:39] op_sel_hi:[1,0]
	v_pk_mul_f32 v[6:7], v[6:7], v[38:39] op_sel_hi:[1,0]
	v_pk_mul_f32 v[8:9], v[8:9], v[38:39] op_sel_hi:[1,0]
	v_pk_mul_f32 v[2:3], v[34:35], v[2:3]
	v_pk_mul_f32 v[4:5], v[36:37], v[4:5]
	v_cvt_pk_bf16_f32 v2, v2, v3
	v_cvt_pk_bf16_f32 v3, v4, v5
	global_store_dwordx2 v[18:19], v[2:3], off offset:-1536
	v_mov_b64_e32 v[2:3], v[148:149]
	v_mov_b64_e32 v[4:5], v[150:151]
	v_mov_b32_e32 v34, v24
	v_mov_b32_e32 v35, v22
	v_mov_b32_e32 v22, v25
	v_pk_mul_f32 v[24:25], v[34:35], v[38:39] op_sel_hi:[1,0]
	v_pk_mul_f32 v[22:23], v[22:23], v[38:39] op_sel_hi:[1,0]
	v_pk_mul_f32 v[2:3], v[2:3], v[24:25]
	v_pk_mul_f32 v[4:5], v[4:5], v[22:23]
	v_cvt_pk_bf16_f32 v2, v2, v3
	v_cvt_pk_bf16_f32 v3, v4, v5
	global_store_dwordx2 v[18:19], v[2:3], off offset:-1024
	v_mov_b64_e32 v[2:3], v[152:153]
	v_mov_b64_e32 v[4:5], v[154:155]
	v_pk_mul_f32 v[2:3], v[6:7], v[2:3]
	v_pk_mul_f32 v[4:5], v[8:9], v[4:5]
	v_cvt_pk_bf16_f32 v2, v2, v3
	v_cvt_pk_bf16_f32 v3, v4, v5
	global_store_dwordx2 v[18:19], v[2:3], off offset:-512
	v_mov_b64_e32 v[2:3], v[156:157]
	v_mov_b64_e32 v[4:5], v[158:159]
	v_pk_mul_f32 v[6:7], v[10:11], v[38:39] op_sel_hi:[1,0]
	v_pk_mul_f32 v[8:9], v[12:13], v[38:39] op_sel_hi:[1,0]
	v_pk_mul_f32 v[2:3], v[6:7], v[2:3]
	v_pk_mul_f32 v[4:5], v[8:9], v[4:5]
	v_cvt_pk_bf16_f32 v2, v2, v3
	v_cvt_pk_bf16_f32 v3, v4, v5
	global_store_dwordx2 v[18:19], v[2:3], off
	s_branch .LBB0_1119

; __device__ __forceinline__ void resnorm_rows(const float* hin, const bf16_t* tmp, const float* g1, float* hout, const float* g2, bf16_t* xn, int gw, int NGW, int lane) {
;     for (int row = gw; row < NTOK; row += NGW) {
;         const u32x2* tr = (const u32x2*)(tmp + (size_t)row * DMODEL) + lane; f32x4 t[4]; float ss = 0.f;
; #pragma unroll
;         for (int j = 0; j < 4; ++j) { const u32x2 w = __builtin_nontemporal_load(tr + 64 * j); t[j] = (f32x4){bflo(w.x), bfhi(w.x), bflo(w.y), bfhi(w.y)}; ss += (t[j][0] * t[j][0] + t[j][1] * t[j][1]) + (t[j][2] * t[j][2] + t[j][3] * t[j][3]); }
;         const float rs = __builtin_amdgcn_rsqf(wave_sum(ss) * (1.f / DMODEL) + EPSN);
.Lrn_nopf_ph10:
	v_lshlrev_b32_e32 v45, 16, v37
	v_and_b32_e32 v47, 0xffff0000, v37
	v_and_b32_e32 v46, 0xffff0000, v36
	v_lshlrev_b32_e32 v50, 16, v39
	v_and_b32_e32 v51, 0xffff0000, v39
	v_and_b32_e32 v37, 0xffff0000, v40
	v_and_b32_e32 v39, 0xffff0000, v41
	v_lshlrev_b32_e32 v44, 16, v36
	v_lshlrev_b32_e32 v48, 16, v38
	v_and_b32_e32 v49, 0xffff0000, v38
	v_lshlrev_b32_e32 v36, 16, v40
	v_lshlrev_b32_e32 v38, 16, v41
	v_pk_mul_f32 v[40:41], v[46:47], v[46:47]
	v_mul_f32_e32 v60, v37, v37
	v_mul_f32_e32 v62, v39, v39
	v_lshlrev_b32_e32 v52, 16, v42
	v_and_b32_e32 v55, 0xffff0000, v42
	v_and_b32_e32 v54, s0, v42
	v_lshlrev_b32_e32 v56, 16, v43
	v_and_b32_e32 v57, 0xffff0000, v43
	v_mul_f32_e32 v42, v49, v49
	v_mul_f32_e32 v58, v51, v51
	v_pk_fma_f32 v[40:41], v[44:45], v[44:45], v[40:41]
	v_pk_fma_f32 v[60:61], v[36:37], v[36:37], v[60:61] op_sel_hi:[1,1,0]
	v_pk_fma_f32 v[62:63], v[38:39], v[38:39], v[62:63] op_sel_hi:[1,1,0]
	v_pk_mul_f32 v[64:65], v[54:55], v[54:55]
	v_pk_mul_f32 v[66:67], v[56:57], v[56:57]
	v_pk_fma_f32 v[42:43], v[48:49], v[48:49], v[42:43] op_sel_hi:[1,1,0]
	v_pk_fma_f32 v[58:59], v[50:51], v[50:51], v[58:59] op_sel_hi:[1,1,0]
	v_pk_add_f32 v[40:41], v[40:41], v[40:41] op_sel:[0,1] op_sel_hi:[1,0]
	v_pk_add_f32 v[60:61], v[60:61], v[62:63]
	v_mov_b32_e32 v43, v66
	v_mov_b32_e32 v59, v67
	v_mul_f32_e32 v61, v52, v52
	v_mov_b32_e32 v41, v65
	v_pk_add_f32 v[42:43], v[42:43], v[58:59]
	v_pk_add_f32 v[40:41], v[60:61], v[40:41]
	v_mov_b32_e32 v53, v55
	v_pk_add_f32 v[40:41], v[40:41], v[42:43]
	v_mov_b32_e32 v42, v44
	v_add_f32_e32 v25, v40, v41
	ds_bpermute_b32 v35, v19, v25
	v_mov_b32_e32 v43, v46
	v_mov_b32_e32 v46, v45
	v_lshl_add_u64 v[40:41], v[16:17], 0, s[16:17]
	s_waitcnt lgkmcnt(0)
	v_add_f32_e32 v25, v25, v35
	ds_bpermute_b32 v35, v20, v25
	s_waitcnt lgkmcnt(0)
	v_add_f32_e32 v25, v25, v35
	ds_bpermute_b32 v35, v21, v25
	s_waitcnt lgkmcnt(0)
	v_add_f32_e32 v25, v25, v35
	ds_bpermute_b32 v35, v22, v25
	s_waitcnt lgkmcnt(0)
	v_add_f32_e32 v25, v25, v35
	ds_bpermute_b32 v35, v23, v25
	s_waitcnt lgkmcnt(0)
	v_add_f32_e32 v25, v25, v35
	ds_bpermute_b32 v35, v24, v25
	s_waitcnt lgkmcnt(0)
; __device__ __forceinline__ unsigned cvtpk(float lo, float hi) { typedef __bf16 bf2 __attribute__((ext_vector_type(2))); f32x2 v = {lo, hi}; bf2 b = __builtin_convertvector(v, bf2); return __builtin_bit_cast(unsigned, b); }
; __device__ __forceinline__ void st16_wt(void* p, u32x4 v) { asm volatile("global_store_dwordx4 %0, %1, off sc1\n\ts_nop 4" :: "v"(p), "v"(v) : "memory"); }
; __device__ __forceinline__ void resnorm_rows(const float* hin, const bf16_t* tmp, const float* g1, float* hout, const float* g2, bf16_t* xn, int gw, int NGW, int lane) {
;     ...
;         const float rs = __builtin_amdgcn_rsqf(wave_sum(ss) * (1.f / DMODEL) + EPSN);
;         const f32x4* hr = (const f32x4*)(hin + (size_t)row * DMODEL) + lane; f32x4* ho = (f32x4*)(hout + (size_t)row * DMODEL) + lane; float s2 = 0.f;
; #pragma unroll
;         for (int j = 0; j < 4; ++j) { const f32x4 gg = ((const f32x4*)g1)[lane + 64 * j]; f32x4 h = __builtin_nontemporal_load(hr + 64 * j);
;             h[0] += t[j][0] * rs * gg[0]; h[1] += t[j][1] * rs * gg[1]; h[2] += t[j][2] * rs * gg[2]; h[3] += t[j][3] * rs * gg[3];
;             st16_wt(ho + 64 * j, __builtin_bit_cast(u32x4, h)); t[j] = h; s2 += (h[0] * h[0] + h[1] * h[1]) + (h[2] * h[2] + h[3] * h[3]); }
;         if (g2) {
;             const float r2 = __builtin_amdgcn_rsqf(wave_sum(s2) * (1.f / DMODEL) + EPSN);
;             u32x2* o = (u32x2*)(xn + (size_t)row * DMODEL) + lane;
; #pragma unroll
;             for (int j = 0; j < 4; ++j) { const f32x4 gg = ((const f32x4*)g2)[lane + 64 * j]; u32x2 w; w.x = cvtpk(t[j][0] * r2 * gg[0], t[j][1] * r2 * gg[1]); w.y = cvtpk(t[j][2] * r2 * gg[2], t[j][3] * r2 * gg[3]); o[64 * j] = w; }
;         }
	v_add_f32_e32 v25, v25, v35
	v_fmamk_f32 v25, v25, 0x3a800000, v5
	v_rsq_f32_e32 v54, v25
	s_nop 0
	v_pk_mul_f32 v[36:37], v[54:55], v[36:37] op_sel_hi:[0,1]
	v_pk_mul_f32 v[38:39], v[54:55], v[38:39] op_sel_hi:[0,1]
	v_pk_fma_f32 v[26:27], v[26:27], v[36:37], v[30:31]
	v_pk_fma_f32 v[28:29], v[28:29], v[38:39], v[32:33]
	v_pk_mul_f32 v[42:43], v[54:55], v[42:43] op_sel_hi:[0,1]
	global_store_dwordx4 v[16:17], v[26:29], off nt
	s_nop 4
	v_mov_b64_e32 v[30:31], v[120:121]
	v_mov_b64_e32 v[32:33], v[122:123]
	v_mov_b64_e32 v[36:37], v[124:125]
	v_mov_b64_e32 v[38:39], v[126:127]
	v_pk_mul_f32 v[44:45], v[54:55], v[46:47] op_sel_hi:[0,1]
	v_pk_mul_f32 v[46:47], v[54:55], v[48:49] op_sel_hi:[0,1]
	v_pk_mul_f32 v[48:49], v[54:55], v[50:51] op_sel_hi:[0,1]
	v_pk_mul_f32 v[50:51], v[54:55], v[52:53] op_sel_hi:[0,1]
	v_pk_mul_f32 v[52:53], v[54:55], v[56:57] op_sel_hi:[0,1]
	v_pk_fma_f32 v[30:31], v[30:31], v[42:43], v[36:37]
	v_pk_fma_f32 v[32:33], v[32:33], v[44:45], v[38:39]
	v_lshl_add_u64 v[44:45], v[16:17], 0, s[18:19]
	global_store_dwordx4 v[40:41], v[30:33], off nt
	s_nop 4
	v_mov_b64_e32 v[36:37], v[128:129]
	v_mov_b64_e32 v[38:39], v[130:131]
	v_mov_b64_e32 v[40:41], v[132:133]
	v_mov_b64_e32 v[42:43], v[134:135]
	v_pk_fma_f32 v[36:37], v[36:37], v[46:47], v[40:41]
	v_pk_fma_f32 v[38:39], v[38:39], v[48:49], v[42:43]
	v_lshl_add_u64 v[48:49], v[16:17], 0, s[20:21]
	global_store_dwordx4 v[44:45], v[36:39], off nt
	s_nop 4
	v_mov_b64_e32 v[40:41], v[136:137]
	v_mov_b64_e32 v[42:43], v[138:139]
	v_mov_b64_e32 v[44:45], v[140:141]
	v_mov_b64_e32 v[46:47], v[142:143]
	v_lshl_add_u64 v[16:17], v[16:17], 0, s[10:11]
	v_pk_fma_f32 v[40:41], v[50:51], v[40:41], v[44:45]
	v_pk_fma_f32 v[42:43], v[52:53], v[42:43], v[46:47]
	v_mov_b32_e32 v50, v27
	global_store_dwordx4 v[48:49], v[40:43], off nt
	s_nop 4
	v_mov_b64_e32 v[44:45], v[144:145]
	v_mov_b64_e32 v[46:47], v[146:147]
	v_mov_b32_e32 v51, v29
	v_mov_b32_e32 v48, v26
	v_mov_b32_e32 v49, v28
	v_pk_mul_f32 v[50:51], v[50:51], v[50:51]
	v_mov_b32_e32 v52, v31
	v_mov_b32_e32 v53, v33
	v_pk_fma_f32 v[48:49], v[48:49], v[48:49], v[50:51]
	v_mov_b32_e32 v50, v30
	v_mov_b32_e32 v51, v32
	v_pk_mul_f32 v[52:53], v[52:53], v[52:53]
	v_pk_add_f32 v[48:49], v[48:49], v[48:49] op_sel_hi:[0,1]
	v_pk_fma_f32 v[50:51], v[50:51], v[50:51], v[52:53]
	v_mul_f32_e32 v48, v36, v36
	v_pk_add_f32 v[50:51], v[50:51], v[50:51] op_sel_hi:[0,1]
	v_mul_f32_e32 v50, v38, v38
	v_pk_fma_f32 v[52:53], v[36:37], v[36:37], v[48:49] op_sel_hi:[1,1,0]
	v_pk_fma_f32 v[54:55], v[38:39], v[38:39], v[50:51] op_sel_hi:[1,1,0]
	v_pk_mul_f32 v[56:57], v[40:41], v[40:41]
	v_pk_mul_f32 v[58:59], v[42:43], v[42:43]
	v_mov_b32_e32 v52, v56
	v_mov_b32_e32 v54, v57
	v_mov_b32_e32 v48, v58
	v_mov_b32_e32 v50, v59
	v_pk_add_f32 v[52:53], v[52:53], v[54:55]
	v_pk_add_f32 v[48:49], v[48:49], v[50:51]
	s_nop 0
	v_pk_add_f32 v[48:49], v[52:53], v[48:49]
	s_nop 0
	v_add_f32_e32 v25, v48, v49
	ds_bpermute_b32 v35, v19, v25
	s_waitcnt lgkmcnt(0)
	v_add_f32_e32 v25, v25, v35
	ds_bpermute_b32 v35, v20, v25
	s_waitcnt lgkmcnt(0)
	v_add_f32_e32 v25, v25, v35
	ds_bpermute_b32 v35, v21, v25
	s_waitcnt lgkmcnt(0)
	v_add_f32_e32 v25, v25, v35
	ds_bpermute_b32 v35, v22, v25
	s_waitcnt lgkmcnt(0)
	v_add_f32_e32 v25, v25, v35
	ds_bpermute_b32 v35, v23, v25
	s_waitcnt lgkmcnt(0)
	v_add_f32_e32 v25, v25, v35
	ds_bpermute_b32 v35, v24, v25
	s_waitcnt lgkmcnt(0)
	v_add_f32_e32 v25, v25, v35
	v_fmamk_f32 v25, v25, 0x3a800000, v5
	v_rsq_f32_e32 v48, v25
	s_nop 0
	v_pk_mul_f32 v[26:27], v[26:27], v[48:49] op_sel_hi:[1,0]
	v_pk_mul_f32 v[28:29], v[28:29], v[48:49] op_sel_hi:[1,0]
	v_pk_mul_f32 v[30:31], v[30:31], v[48:49] op_sel_hi:[1,0]
	v_pk_mul_f32 v[32:33], v[32:33], v[48:49] op_sel_hi:[1,0]
	v_pk_mul_f32 v[26:27], v[44:45], v[26:27]
	v_pk_mul_f32 v[28:29], v[46:47], v[28:29]
	v_cvt_pk_bf16_f32 v26, v26, v27
	v_cvt_pk_bf16_f32 v27, v28, v29
	global_store_dwordx2 v[14:15], v[26:27], off offset:-1024
	v_mov_b64_e32 v[26:27], v[148:149]
	v_mov_b64_e32 v[28:29], v[150:151]
	v_pk_mul_f32 v[26:27], v[26:27], v[30:31]
	v_pk_mul_f32 v[28:29], v[28:29], v[32:33]
	v_cvt_pk_bf16_f32 v26, v26, v27
	v_cvt_pk_bf16_f32 v27, v28, v29
	global_store_dwordx2 v[14:15], v[26:27], off offset:-512
	v_mov_b64_e32 v[26:27], v[152:153]
	v_mov_b64_e32 v[28:29], v[154:155]
	v_pk_mul_f32 v[30:31], v[36:37], v[48:49] op_sel_hi:[1,0]
	v_pk_mul_f32 v[32:33], v[38:39], v[48:49] op_sel_hi:[1,0]
	v_pk_mul_f32 v[26:27], v[26:27], v[30:31]
	v_pk_mul_f32 v[28:29], v[28:29], v[32:33]
	v_cvt_pk_bf16_f32 v26, v26, v27
	v_cvt_pk_bf16_f32 v27, v28, v29
	global_store_dwordx2 v[14:15], v[26:27], off
	v_mov_b64_e32 v[26:27], v[156:157]
	v_mov_b64_e32 v[28:29], v[158:159]
	v_pk_mul_f32 v[30:31], v[40:41], v[48:49] op_sel_hi:[1,0]
	v_pk_mul_f32 v[32:33], v[42:43], v[48:49] op_sel_hi:[1,0]
	v_pk_mul_f32 v[26:27], v[26:27], v[30:31]
	v_pk_mul_f32 v[28:29], v[28:29], v[32:33]
	v_cvt_pk_bf16_f32 v26, v26, v27
	v_cvt_pk_bf16_f32 v27, v28, v29
	global_store_dwordx2 v[14:15], v[26:27], off offset:512
	v_lshl_add_u64 v[14:15], v[14:15], 0, s[8:9]
	s_cbranch_scc1 .LBB0_1441

; __device__ __forceinline__ void resnorm_rows(const float* hin, const bf16_t* tmp, const float* g1, float* hout, const float* g2, bf16_t* xn, int gw, int NGW, int lane) {
;     for (int row = gw; row < NTOK; row += NGW) {
;         const u32x2* tr = (const u32x2*)(tmp + (size_t)row * DMODEL) + lane; f32x4 t[4]; float ss = 0.f;
; #pragma unroll
;         for (int j = 0; j < 4; ++j) { const u32x2 w = __builtin_nontemporal_load(tr + 64 * j); t[j] = (f32x4){bflo(w.x), bfhi(w.x), bflo(w.y), bfhi(w.y)}; ss += (t[j][0] * t[j][0] + t[j][1] * t[j][1]) + (t[j][2] * t[j][2] + t[j][3] * t[j][3]); }
;         const float rs = __builtin_amdgcn_rsqf(wave_sum(ss) * (1.f / DMODEL) + EPSN);
.Lrn_nopf_ph17:
	v_lshlrev_b32_e32 v49, 16, v41
	v_and_b32_e32 v51, 0xffff0000, v41
	v_and_b32_e32 v50, 0xffff0000, v40
	v_and_b32_e32 v39, 0xffff0000, v44
	v_and_b32_e32 v41, 0xffff0000, v45
	v_lshlrev_b32_e32 v48, 16, v40
	v_lshlrev_b32_e32 v52, 16, v42
	v_and_b32_e32 v53, 0xffff0000, v42
	v_lshlrev_b32_e32 v54, 16, v43
	v_and_b32_e32 v55, 0xffff0000, v43
	v_lshlrev_b32_e32 v38, 16, v44
	v_lshlrev_b32_e32 v40, 16, v45
	v_pk_mul_f32 v[42:43], v[50:51], v[50:51]
	v_mul_f32_e32 v62, v39, v39
	v_mul_f32_e32 v64, v41, v41
	v_lshlrev_b32_e32 v56, 16, v46
	v_and_b32_e32 v59, 0xffff0000, v46
	v_and_b32_e32 v58, s0, v46
	v_lshlrev_b32_e32 v60, 16, v47
	v_and_b32_e32 v61, 0xffff0000, v47
	v_mul_f32_e32 v44, v53, v53
	v_mul_f32_e32 v46, v55, v55
	v_pk_fma_f32 v[42:43], v[48:49], v[48:49], v[42:43]
	v_pk_fma_f32 v[62:63], v[38:39], v[38:39], v[62:63] op_sel_hi:[1,1,0]
	v_pk_fma_f32 v[64:65], v[40:41], v[40:41], v[64:65] op_sel_hi:[1,1,0]
	v_pk_mul_f32 v[66:67], v[58:59], v[58:59]
	v_pk_mul_f32 v[68:69], v[60:61], v[60:61]
	v_pk_fma_f32 v[44:45], v[52:53], v[52:53], v[44:45] op_sel_hi:[1,1,0]
	v_pk_fma_f32 v[46:47], v[54:55], v[54:55], v[46:47] op_sel_hi:[1,1,0]
	v_pk_add_f32 v[42:43], v[42:43], v[42:43] op_sel:[0,1] op_sel_hi:[1,0]
	v_pk_add_f32 v[62:63], v[62:63], v[64:65]
	v_mov_b32_e32 v45, v68
	v_mov_b32_e32 v47, v69
	v_mul_f32_e32 v63, v56, v56
	v_mov_b32_e32 v43, v67
	v_pk_add_f32 v[44:45], v[44:45], v[46:47]
	v_pk_add_f32 v[42:43], v[62:63], v[42:43]
	v_mov_b32_e32 v57, v59
	v_pk_add_f32 v[42:43], v[42:43], v[44:45]
	v_mov_b32_e32 v44, v48
	v_add_f32_e32 v29, v42, v43
	ds_bpermute_b32 v42, v22, v29
	v_mov_b32_e32 v45, v50
	v_mov_b32_e32 v50, v49
	s_waitcnt lgkmcnt(0)
	v_add_f32_e32 v29, v29, v42
	ds_bpermute_b32 v42, v23, v29
	s_waitcnt lgkmcnt(0)
	v_add_f32_e32 v29, v29, v42
	ds_bpermute_b32 v42, v24, v29
	s_waitcnt lgkmcnt(0)
	v_add_f32_e32 v29, v29, v42
	ds_bpermute_b32 v42, v25, v29
	s_waitcnt lgkmcnt(0)
	v_add_f32_e32 v29, v29, v42
	ds_bpermute_b32 v42, v26, v29
	s_waitcnt lgkmcnt(0)
	v_add_f32_e32 v29, v29, v42
	ds_bpermute_b32 v42, v27, v29
	s_waitcnt lgkmcnt(0)
; __device__ __forceinline__ unsigned cvtpk(float lo, float hi) { typedef __bf16 bf2 __attribute__((ext_vector_type(2))); f32x2 v = {lo, hi}; bf2 b = __builtin_convertvector(v, bf2); return __builtin_bit_cast(unsigned, b); }
; __device__ __forceinline__ void st16_wt(void* p, u32x4 v) { asm volatile("global_store_dwordx4 %0, %1, off sc1\n\ts_nop 4" :: "v"(p), "v"(v) : "memory"); }
; __device__ __forceinline__ void resnorm_rows(const float* hin, const bf16_t* tmp, const float* g1, float* hout, const float* g2, bf16_t* xn, int gw, int NGW, int lane) {
;     ...
;         const float rs = __builtin_amdgcn_rsqf(wave_sum(ss) * (1.f / DMODEL) + EPSN);
;         const f32x4* hr = (const f32x4*)(hin + (size_t)row * DMODEL) + lane; f32x4* ho = (f32x4*)(hout + (size_t)row * DMODEL) + lane; float s2 = 0.f;
; #pragma unroll
;         for (int j = 0; j < 4; ++j) { const f32x4 gg = ((const f32x4*)g1)[lane + 64 * j]; f32x4 h = __builtin_nontemporal_load(hr + 64 * j);
;             h[0] += t[j][0] * rs * gg[0]; h[1] += t[j][1] * rs * gg[1]; h[2] += t[j][2] * rs * gg[2]; h[3] += t[j][3] * rs * gg[3];
;             st16_wt(ho + 64 * j, __builtin_bit_cast(u32x4, h)); t[j] = h; s2 += (h[0] * h[0] + h[1] * h[1]) + (h[2] * h[2] + h[3] * h[3]); }
;         if (g2) {
;             const float r2 = __builtin_amdgcn_rsqf(wave_sum(s2) * (1.f / DMODEL) + EPSN);
;             u32x2* o = (u32x2*)(xn + (size_t)row * DMODEL) + lane;
; #pragma unroll
;             for (int j = 0; j < 4; ++j) { const f32x4 gg = ((const f32x4*)g2)[lane + 64 * j]; u32x2 w; w.x = cvtpk(t[j][0] * r2 * gg[0], t[j][1] * r2 * gg[1]); w.y = cvtpk(t[j][2] * r2 * gg[2], t[j][3] * r2 * gg[3]); o[64 * j] = w; }
;         }
	v_add_f32_e32 v29, v29, v42
	v_fmamk_f32 v29, v29, 0x3a800000, v28
	v_rsq_f32_e32 v58, v29
	v_lshl_add_u64 v[42:43], v[20:21], 0, s[8:9]
	v_pk_mul_f32 v[38:39], v[58:59], v[38:39] op_sel_hi:[0,1]
	v_pk_mul_f32 v[40:41], v[58:59], v[40:41] op_sel_hi:[0,1]
	v_pk_fma_f32 v[30:31], v[30:31], v[38:39], v[34:35]
	v_pk_fma_f32 v[32:33], v[32:33], v[40:41], v[36:37]
	v_pk_mul_f32 v[44:45], v[58:59], v[44:45] op_sel_hi:[0,1]
	global_store_dwordx4 v[20:21], v[30:33], off nt
	s_nop 4
	v_mov_b64_e32 v[34:35], v[120:121]
	v_mov_b64_e32 v[36:37], v[122:123]
	v_mov_b64_e32 v[38:39], v[124:125]
	v_mov_b64_e32 v[40:41], v[126:127]
	v_pk_mul_f32 v[46:47], v[58:59], v[50:51] op_sel_hi:[0,1]
	v_pk_mul_f32 v[48:49], v[58:59], v[52:53] op_sel_hi:[0,1]
	v_pk_mul_f32 v[50:51], v[58:59], v[54:55] op_sel_hi:[0,1]
	v_pk_mul_f32 v[52:53], v[58:59], v[56:57] op_sel_hi:[0,1]
	v_pk_mul_f32 v[54:55], v[58:59], v[60:61] op_sel_hi:[0,1]
	v_pk_fma_f32 v[34:35], v[34:35], v[44:45], v[38:39]
	v_pk_fma_f32 v[36:37], v[36:37], v[46:47], v[40:41]
	v_lshl_add_u64 v[46:47], v[20:21], 0, s[10:11]
	global_store_dwordx4 v[42:43], v[34:37], off nt
	s_nop 4
	v_mov_b64_e32 v[38:39], v[128:129]
	v_mov_b64_e32 v[40:41], v[130:131]
	v_mov_b64_e32 v[42:43], v[132:133]
	v_mov_b64_e32 v[44:45], v[134:135]
	v_pk_fma_f32 v[38:39], v[38:39], v[48:49], v[42:43]
	v_pk_fma_f32 v[40:41], v[40:41], v[50:51], v[44:45]
	v_lshl_add_u64 v[50:51], v[20:21], 0, s[16:17]
	global_store_dwordx4 v[46:47], v[38:41], off nt
	s_nop 4
	v_mov_b64_e32 v[42:43], v[136:137]
	v_mov_b64_e32 v[44:45], v[138:139]
	v_mov_b64_e32 v[46:47], v[140:141]
	v_mov_b64_e32 v[48:49], v[142:143]
	v_lshl_add_u64 v[20:21], v[20:21], 0, s[4:5]
	v_pk_fma_f32 v[42:43], v[52:53], v[42:43], v[46:47]
	v_pk_fma_f32 v[44:45], v[54:55], v[44:45], v[48:49]
	v_mov_b32_e32 v52, v31
	global_store_dwordx4 v[50:51], v[42:45], off nt
	s_nop 4
	v_mov_b64_e32 v[46:47], v[144:145]
	v_mov_b64_e32 v[48:49], v[146:147]
	v_mov_b32_e32 v53, v33
	v_mov_b32_e32 v50, v30
	v_mov_b32_e32 v51, v32
	v_pk_mul_f32 v[52:53], v[52:53], v[52:53]
	v_mov_b32_e32 v54, v35
	v_mov_b32_e32 v55, v37
	v_pk_fma_f32 v[50:51], v[50:51], v[50:51], v[52:53]
	v_mov_b32_e32 v52, v34
	v_mov_b32_e32 v53, v36
	v_pk_mul_f32 v[54:55], v[54:55], v[54:55]
	v_pk_add_f32 v[50:51], v[50:51], v[50:51] op_sel_hi:[0,1]
	v_pk_fma_f32 v[52:53], v[52:53], v[52:53], v[54:55]
	v_mul_f32_e32 v50, v38, v38
	v_pk_add_f32 v[52:53], v[52:53], v[52:53] op_sel_hi:[0,1]
	v_mul_f32_e32 v52, v40, v40
	v_pk_fma_f32 v[54:55], v[38:39], v[38:39], v[50:51] op_sel_hi:[1,1,0]
	v_pk_fma_f32 v[56:57], v[40:41], v[40:41], v[52:53] op_sel_hi:[1,1,0]
	v_pk_mul_f32 v[58:59], v[42:43], v[42:43]
	v_pk_mul_f32 v[60:61], v[44:45], v[44:45]
	v_mov_b32_e32 v54, v58
	v_mov_b32_e32 v56, v59
	v_mov_b32_e32 v50, v60
	v_mov_b32_e32 v52, v61
	v_pk_add_f32 v[54:55], v[54:55], v[56:57]
	v_pk_add_f32 v[50:51], v[50:51], v[52:53]
	s_nop 0
	v_pk_add_f32 v[50:51], v[54:55], v[50:51]
	s_nop 0
	v_add_f32_e32 v29, v50, v51
	ds_bpermute_b32 v50, v22, v29
	s_waitcnt lgkmcnt(0)
	v_add_f32_e32 v29, v29, v50
	ds_bpermute_b32 v50, v23, v29
	s_waitcnt lgkmcnt(0)
	v_add_f32_e32 v29, v29, v50
	ds_bpermute_b32 v50, v24, v29
	s_waitcnt lgkmcnt(0)
	v_add_f32_e32 v29, v29, v50
	ds_bpermute_b32 v50, v25, v29
	s_waitcnt lgkmcnt(0)
	v_add_f32_e32 v29, v29, v50
	ds_bpermute_b32 v50, v26, v29
	s_waitcnt lgkmcnt(0)
	v_add_f32_e32 v29, v29, v50
	ds_bpermute_b32 v50, v27, v29
	s_waitcnt lgkmcnt(0)
	v_add_f32_e32 v29, v29, v50
	v_fmamk_f32 v29, v29, 0x3a800000, v28
	v_rsq_f32_e32 v50, v29
	s_nop 0
	v_pk_mul_f32 v[30:31], v[30:31], v[50:51] op_sel_hi:[1,0]
	v_pk_mul_f32 v[32:33], v[32:33], v[50:51] op_sel_hi:[1,0]
	v_pk_mul_f32 v[34:35], v[34:35], v[50:51] op_sel_hi:[1,0]
	v_pk_mul_f32 v[36:37], v[36:37], v[50:51] op_sel_hi:[1,0]
	v_pk_mul_f32 v[30:31], v[46:47], v[30:31]
	v_pk_mul_f32 v[32:33], v[48:49], v[32:33]
	v_cvt_pk_bf16_f32 v30, v30, v31
	v_cvt_pk_bf16_f32 v31, v32, v33
	global_store_dwordx2 v[18:19], v[30:31], off offset:-1536
	v_mov_b64_e32 v[30:31], v[148:149]
	v_mov_b64_e32 v[32:33], v[150:151]
	v_pk_mul_f32 v[30:31], v[30:31], v[34:35]
	v_pk_mul_f32 v[32:33], v[32:33], v[36:37]
	v_cvt_pk_bf16_f32 v30, v30, v31
	v_cvt_pk_bf16_f32 v31, v32, v33
	global_store_dwordx2 v[18:19], v[30:31], off offset:-1024
	v_mov_b64_e32 v[30:31], v[152:153]
	v_mov_b64_e32 v[32:33], v[154:155]
	v_pk_mul_f32 v[34:35], v[38:39], v[50:51] op_sel_hi:[1,0]
	v_pk_mul_f32 v[36:37], v[40:41], v[50:51] op_sel_hi:[1,0]
	v_pk_mul_f32 v[30:31], v[30:31], v[34:35]
	v_pk_mul_f32 v[32:33], v[32:33], v[36:37]
	v_cvt_pk_bf16_f32 v30, v30, v31
	v_cvt_pk_bf16_f32 v31, v32, v33
	global_store_dwordx2 v[18:19], v[30:31], off offset:-512
	v_mov_b64_e32 v[30:31], v[156:157]
	v_mov_b64_e32 v[32:33], v[158:159]
	v_pk_mul_f32 v[34:35], v[42:43], v[50:51] op_sel_hi:[1,0]
	v_pk_mul_f32 v[36:37], v[44:45], v[50:51] op_sel_hi:[1,0]
	v_pk_mul_f32 v[30:31], v[30:31], v[34:35]
	v_pk_mul_f32 v[32:33], v[32:33], v[36:37]
	v_cvt_pk_bf16_f32 v30, v30, v31
	v_cvt_pk_bf16_f32 v31, v32, v33
	global_store_dwordx2 v[18:19], v[30:31], off
	v_lshl_add_u64 v[18:19], v[18:19], 0, s[6:7]
	s_cbranch_scc1 .LBB0_2547

; __device__ __forceinline__ void st16_wt(void* p, u32x4 v) { asm volatile("global_store_dwordx4 %0, %1, off sc1\n\ts_nop 4" :: "v"(p), "v"(v) : "memory"); }
; __device__ __forceinline__ void resnorm_rows(const float* hin, const bf16_t* tmp, const float* g1, float* hout, const float* g2, bf16_t* xn, int gw, int NGW, int lane) {
;     for (int row = gw; row < NTOK; row += NGW) {
;         const u32x2* tr = (const u32x2*)(tmp + (size_t)row * DMODEL) + lane; f32x4 t[4]; float ss = 0.f;
; #pragma unroll
;         for (int j = 0; j < 4; ++j) { const u32x2 w = __builtin_nontemporal_load(tr + 64 * j); t[j] = (f32x4){bflo(w.x), bfhi(w.x), bflo(w.y), bfhi(w.y)}; ss += (t[j][0] * t[j][0] + t[j][1] * t[j][1]) + (t[j][2] * t[j][2] + t[j][3] * t[j][3]); }
;         const float rs = __builtin_amdgcn_rsqf(wave_sum(ss) * (1.f / DMODEL) + EPSN);
;         const f32x4* hr = (const f32x4*)(hin + (size_t)row * DMODEL) + lane; f32x4* ho = (f32x4*)(hout + (size_t)row * DMODEL) + lane; float s2 = 0.f;
; #pragma unroll
;         for (int j = 0; j < 4; ++j) { const f32x4 gg = ((const f32x4*)g1)[lane + 64 * j]; f32x4 h = __builtin_nontemporal_load(hr + 64 * j);
;             h[0] += t[j][0] * rs * gg[0]; h[1] += t[j][1] * rs * gg[1]; h[2] += t[j][2] * rs * gg[2]; h[3] += t[j][3] * rs * gg[3];
;             st16_wt(ho + 64 * j, __builtin_bit_cast(u32x4, h)); t[j] = h; s2 += (h[0] * h[0] + h[1] * h[1]) + (h[2] * h[2] + h[3] * h[3]); }
.Lrn_nopf_ph20:
	v_lshlrev_b32_e32 v33, 16, v25
	v_lshlrev_b32_e32 v32, 16, v24
	v_and_b32_e32 v25, 0xffff0000, v25
	v_and_b32_e32 v24, 0xffff0000, v24
	v_lshlrev_b32_e32 v36, 16, v28
	v_and_b32_e32 v37, 0xffff0000, v28
	v_lshlrev_b32_e32 v28, 16, v29
	v_and_b32_e32 v29, 0xffff0000, v29
	v_lshlrev_b32_e32 v34, 16, v26
	v_and_b32_e32 v35, 0xffff0000, v26
	v_lshlrev_b32_e32 v26, 16, v27
	v_and_b32_e32 v27, 0xffff0000, v27
	v_pk_mul_f32 v[42:43], v[24:25], v[24:25]
	v_mul_f32_e32 v48, v37, v37
	v_mul_f32_e32 v50, v29, v29
	v_lshlrev_b32_e32 v38, 16, v30
	v_and_b32_e32 v41, 0xffff0000, v30
	v_and_b32_e32 v40, s0, v30
	v_lshlrev_b32_e32 v30, 16, v31
	v_and_b32_e32 v31, 0xffff0000, v31
	v_mul_f32_e32 v44, v35, v35
	v_mul_f32_e32 v46, v27, v27
	v_pk_fma_f32 v[42:43], v[32:33], v[32:33], v[42:43]
	v_pk_fma_f32 v[48:49], v[36:37], v[36:37], v[48:49] op_sel_hi:[1,1,0]
	v_pk_fma_f32 v[50:51], v[28:29], v[28:29], v[50:51] op_sel_hi:[1,1,0]
	v_pk_mul_f32 v[52:53], v[40:41], v[40:41]
	v_pk_mul_f32 v[54:55], v[30:31], v[30:31]
	v_pk_fma_f32 v[44:45], v[34:35], v[34:35], v[44:45] op_sel_hi:[1,1,0]
	v_pk_fma_f32 v[46:47], v[26:27], v[26:27], v[46:47] op_sel_hi:[1,1,0]
	v_pk_add_f32 v[42:43], v[42:43], v[42:43] op_sel:[0,1] op_sel_hi:[1,0]
	v_pk_add_f32 v[48:49], v[48:49], v[50:51]
	v_mov_b32_e32 v45, v54
	v_mov_b32_e32 v47, v55
	v_mul_f32_e32 v49, v38, v38
	v_mov_b32_e32 v43, v53
	v_pk_add_f32 v[44:45], v[44:45], v[46:47]
	v_pk_add_f32 v[42:43], v[48:49], v[42:43]
	s_nop 0
	v_pk_add_f32 v[42:43], v[42:43], v[44:45]
	s_nop 0
	v_add_f32_e32 v15, v42, v43
	ds_bpermute_b32 v39, v8, v15
	s_waitcnt lgkmcnt(0)
	v_add_f32_e32 v15, v15, v39
	ds_bpermute_b32 v39, v9, v15
	s_waitcnt lgkmcnt(0)
	v_add_f32_e32 v15, v15, v39
	ds_bpermute_b32 v39, v10, v15
	s_waitcnt lgkmcnt(0)
	v_add_f32_e32 v15, v15, v39
	ds_bpermute_b32 v39, v11, v15
	s_waitcnt lgkmcnt(0)
	v_add_f32_e32 v15, v15, v39
	ds_bpermute_b32 v39, v12, v15
	s_waitcnt lgkmcnt(0)
	v_add_f32_e32 v15, v15, v39
	ds_bpermute_b32 v39, v13, v15
	s_waitcnt lgkmcnt(0)
	v_add_f32_e32 v15, v15, v39
	v_fmamk_f32 v15, v15, 0x3a800000, v14
	v_rsq_f32_e32 v40, v15
	v_mov_b32_e32 v39, v41
	v_pk_mul_f32 v[36:37], v[40:41], v[36:37] op_sel_hi:[0,1]
	v_pk_mul_f32 v[28:29], v[40:41], v[28:29] op_sel_hi:[0,1]
	v_pk_fma_f32 v[18:19], v[18:19], v[28:29], v[22:23]
	v_pk_fma_f32 v[16:17], v[16:17], v[36:37], v[20:21]
	v_mov_b32_e32 v36, v32
	global_store_dwordx4 v[6:7], v[16:19], off nt
	s_nop 4
	v_mov_b64_e32 v[16:17], v[120:121]
	v_mov_b64_e32 v[18:19], v[122:123]
	v_mov_b64_e32 v[20:21], v[124:125]
	v_mov_b64_e32 v[22:23], v[126:127]
	v_mov_b32_e32 v37, v24
	v_mov_b32_e32 v24, v33
	v_pk_mul_f32 v[32:33], v[40:41], v[36:37] op_sel_hi:[0,1]
	v_pk_mul_f32 v[24:25], v[40:41], v[24:25] op_sel_hi:[0,1]
	v_lshl_add_u64 v[28:29], v[6:7], 0, s[4:5]
	v_pk_mul_f32 v[26:27], v[40:41], v[26:27] op_sel_hi:[0,1]
	v_pk_fma_f32 v[16:17], v[16:17], v[32:33], v[20:21]
	v_pk_fma_f32 v[18:19], v[18:19], v[24:25], v[22:23]
	v_lshl_add_u64 v[24:25], v[6:7], 0, s[6:7]
	global_store_dwordx4 v[28:29], v[16:19], off nt
	s_nop 4
	v_mov_b64_e32 v[16:17], v[128:129]
	v_mov_b64_e32 v[18:19], v[130:131]
	v_mov_b64_e32 v[20:21], v[132:133]
	v_mov_b64_e32 v[22:23], v[134:135]
	v_pk_mul_f32 v[28:29], v[40:41], v[34:35] op_sel_hi:[0,1]
	v_pk_fma_f32 v[16:17], v[16:17], v[28:29], v[20:21]
	v_pk_fma_f32 v[18:19], v[18:19], v[26:27], v[22:23]
	v_pk_mul_f32 v[26:27], v[40:41], v[30:31] op_sel_hi:[0,1]
	global_store_dwordx4 v[24:25], v[16:19], off nt
	s_nop 4
	v_mov_b64_e32 v[16:17], v[136:137]
	v_mov_b64_e32 v[18:19], v[138:139]
	v_mov_b64_e32 v[20:21], v[140:141]
	v_mov_b64_e32 v[22:23], v[142:143]
	v_pk_mul_f32 v[28:29], v[40:41], v[38:39] op_sel_hi:[0,1]
	v_lshl_add_u64 v[24:25], v[6:7], 0, s[8:9]
	v_lshl_add_u64 v[6:7], v[6:7], 0, s[2:3]
	v_pk_fma_f32 v[16:17], v[28:29], v[16:17], v[20:21]
	v_pk_fma_f32 v[18:19], v[26:27], v[18:19], v[22:23]
	s_nop 0
	global_store_dwordx4 v[24:25], v[16:19], off nt
	s_nop 4
	s_cbranch_scc1 .LBB0_2867
